# v92 + mLSTM scan instruction trimming: gate / max arrays stored pre-scaled by log2e (32 fewer multiplies per chunk per wave), staging multiplies read the hoisted decay weights directly (no copies)
# speedup vs baseline: 1.0068x; 1.0068x over previous
.LBB0_204:
	s_or_b64 exec, exec, s[86:87]
	s_andn2_b64 vcc, exec, s[82:83]
	s_waitcnt lgkmcnt(0)
	s_barrier
	s_cbranch_vccnz .LBB0_208
	ds_read_b64 v[72:73], v159
	ds_read_b64 v[76:77], v160
	s_waitcnt lgkmcnt(1)
	v_add_f32_e32 v73, v72, v73
	v_mov_b32_e32 v75, v73
	s_nop 1
	v_add_f32_dpp v75, v75, v75 row_shr:1 row_mask:0xf bank_mask:0xf
	s_nop 1
	v_add_f32_dpp v75, v75, v75 row_shr:2 row_mask:0xf bank_mask:0xf
	s_nop 1
	v_add_f32_dpp v75, v75, v75 row_shr:4 row_mask:0xf bank_mask:0xf
	s_nop 1
	v_add_f32_dpp v75, v75, v75 row_shr:8 row_mask:0xf bank_mask:0xf
	s_nop 1
	v_add_f32_dpp v75, v75, v75 row_bcast:15 row_mask:0xa bank_mask:0xf
	s_nop 1
	v_add_f32_dpp v75, v75, v75 row_bcast:31 row_mask:0xc bank_mask:0xf
	s_waitcnt lgkmcnt(0)
	v_sub_f32_e32 v73, v75, v73
	v_add_f32_e32 v74, v72, v73
	v_pk_add_f32 v[76:77], v[76:77], v[74:75] neg_lo:[0,1] neg_hi:[0,1]
	ds_bpermute_b32 v72, v162, v75
	v_max_f32_e32 v73, v76, v77
	s_nop 1
	v_max_f32_dpp v73, v73, v73 row_shr:1 row_mask:0xf bank_mask:0xf
	s_nop 1
	v_max_f32_dpp v73, v73, v73 row_shr:2 row_mask:0xf bank_mask:0xf
	s_nop 1
	v_max_f32_dpp v73, v73, v73 row_shr:4 row_mask:0xf bank_mask:0xf
	s_nop 1
	v_max_f32_dpp v73, v73, v73 row_shr:8 row_mask:0xf bank_mask:0xf
	s_nop 1
	v_max_f32_dpp v73, v73, v73 row_bcast:15 row_mask:0xa bank_mask:0xf
	s_nop 1
	v_max_f32_dpp v73, v73, v73 row_bcast:31 row_mask:0xc bank_mask:0xf
	s_nop 1
	v_mov_b32_dpp v78, v73 wave_shr:1 row_mask:0xf bank_mask:0xf
	v_max_f32_e32 v73, v73, v73
	v_max_f32_e32 v79, v135, v135
	v_max_f32_e32 v79, v79, v73
	v_add_f32_e32 v75, v75, v79
	s_waitcnt lgkmcnt(0)
	v_cndmask_b32_e64 v78, v78, v218, s[4:5]
	v_max3_f32 v78, v135, v78, v76
	v_add_f32_e32 v74, v74, v78
	v_readlane_b32 s98, v79, 63
	v_mul_f32_e32 v74, 0xbfb8aa3b, v74
	v_mul_f32_e32 v75, 0xbfb8aa3b, v75
	v_exp_f32_e32 v74, v74
	v_exp_f32_e32 v75, v75
	v_mul_f32_e32 v250, 0x3fb8aa3b, v76
	v_mul_f32_e32 v251, 0x3fb8aa3b, v77
	v_mul_f32_e32 v252, 0x3fb8aa3b, v78
	v_mul_f32_e32 v253, 0x3fb8aa3b, v79
	ds_write_b64 v163, v[250:251]
	ds_write_b64 v164, v[252:253]
	v_sub_f32_e32 v80, v135, v78
	v_sub_f32_e32 v81, v135, v79
	ds_write_b64 v166, v[74:75]
	v_mov_b32_e32 v73, s98
	v_sub_f32_e32 v74, v76, v73
	v_sub_f32_e32 v75, v77, v73
	v_mul_f32_e32 v80, 0x3fb8aa3b, v80
	v_mul_f32_e32 v81, 0x3fb8aa3b, v81
	v_mul_f32_e32 v74, 0x3fb8aa3b, v74
	v_mul_f32_e32 v75, 0x3fb8aa3b, v75
	v_exp_f32_e32 v80, v80
	v_exp_f32_e32 v81, v81
	v_exp_f32_e32 v74, v74
	v_exp_f32_e32 v75, v75
	ds_write_b64 v165, v[80:81]
	ds_write_b64 v167, v[74:75]
	s_and_saveexec_b64 s[86:87], s[4:5]
	s_cbranch_execz .LBB0_207
	v_sub_f32_e32 v74, v135, v73
	v_mul_f32_e32 v74, 0x3fb8aa3b, v74
	v_exp_f32_e32 v74, v74
	v_mov_b32_e32 v75, s33
	ds_write_b32 v75, v74

.LBB0_208:
	s_waitcnt lgkmcnt(0)
	s_barrier
	s_waitcnt vmcnt(13)
	ds_write_b128 v189, v[0:3]
	s_waitcnt vmcnt(12)
	ds_write_b128 v189, v[4:7] offset:34816
	s_waitcnt vmcnt(11)
	v_alignbit_b32 v72, v9, v9, 16
	v_alignbit_b32 v73, v8, v8, 16
	v_cndmask_b32_e64 v80, v73, v11, s[2:3]
	v_cndmask_b32_e64 v81, v72, v10, s[2:3]
	ds_read_b128 v[72:75], v156
	v_alignbit_b32 v76, v11, v11, 16
	v_cndmask_b32_e64 v83, v76, v8, s[2:3]
	v_alignbit_b32 v77, v10, v10, 16
	v_lshlrev_b32_e32 v84, 16, v83
	v_and_b32_e32 v83, 0xffff0000, v83
	v_cndmask_b32_e64 v82, v77, v9, s[2:3]
	ds_read_b128 v[76:79], v156 offset:16
	ds_read_b128 v[246:249], v156
	ds_read_b128 v[250:253], v156 offset:16
	s_waitcnt lgkmcnt(1)
	v_mul_f32_e32 v72, v72, v84
	v_mul_f32_e32 v73, v73, v83
	v_cvt_pk_bf16_f32 v72, v72, v73
	v_lshlrev_b32_e32 v73, 16, v82
	v_mul_f32_e32 v73, v74, v73
	v_and_b32_e32 v74, 0xffff0000, v82
	v_mul_f32_e32 v74, v75, v74
	v_cvt_pk_bf16_f32 v73, v73, v74
	v_lshlrev_b32_e32 v74, 16, v81
	v_and_b32_e32 v75, 0xffff0000, v81
	s_waitcnt lgkmcnt(0)
	v_mul_f32_e32 v74, v76, v74
	v_mul_f32_e32 v75, v77, v75
	v_cvt_pk_bf16_f32 v74, v74, v75
	v_lshlrev_b32_e32 v75, 16, v80
	v_mul_f32_e32 v75, v78, v75
	v_and_b32_e32 v76, 0xffff0000, v80
	v_mul_f32_e32 v76, v79, v76
	v_cvt_pk_bf16_f32 v75, v75, v76
	ds_write_b128 v190, v[72:75]
	s_waitcnt vmcnt(10)
	ds_write_b128 v192, v[12:15]
	s_waitcnt vmcnt(9)
	ds_write_b128 v192, v[16:19] offset:34816
	s_waitcnt vmcnt(8)
	v_alignbit_b32 v72, v21, v21, 16
	v_alignbit_b32 v73, v20, v20, 16
	v_cndmask_b32_e64 v80, v73, v23, s[2:3]
	v_cndmask_b32_e64 v81, v72, v22, s[2:3]
	v_alignbit_b32 v76, v23, v23, 16
	v_cndmask_b32_e64 v83, v76, v20, s[2:3]
	v_alignbit_b32 v77, v22, v22, 16
	v_lshlrev_b32_e32 v84, 16, v83
	v_and_b32_e32 v83, 0xffff0000, v83
	v_cndmask_b32_e64 v82, v77, v21, s[2:3]
	v_mul_f32_e32 v72, v246, v84
	v_mul_f32_e32 v73, v247, v83
	v_cvt_pk_bf16_f32 v72, v72, v73
	v_lshlrev_b32_e32 v73, 16, v82
	v_mul_f32_e32 v73, v248, v73
	v_and_b32_e32 v74, 0xffff0000, v82
	v_mul_f32_e32 v74, v249, v74
	v_cvt_pk_bf16_f32 v73, v73, v74
	v_lshlrev_b32_e32 v74, 16, v81
	v_and_b32_e32 v75, 0xffff0000, v81
	v_mul_f32_e32 v74, v250, v74
	v_mul_f32_e32 v75, v251, v75
	v_cvt_pk_bf16_f32 v74, v74, v75
	v_lshlrev_b32_e32 v75, 16, v80
	v_mul_f32_e32 v75, v252, v75
	v_and_b32_e32 v76, 0xffff0000, v80
	v_mul_f32_e32 v76, v253, v76
	v_cvt_pk_bf16_f32 v75, v75, v76
	ds_write_b128 v193, v[72:75]
	s_waitcnt vmcnt(7)
	ds_write_b128 v194, v[24:27]
	s_waitcnt vmcnt(6)
	ds_write_b128 v194, v[28:31] offset:34816
	s_waitcnt vmcnt(5)
	v_alignbit_b32 v72, v33, v33, 16
	v_alignbit_b32 v73, v32, v32, 16
	v_cndmask_b32_e64 v80, v73, v35, s[2:3]
	v_cndmask_b32_e64 v81, v72, v34, s[2:3]
	v_alignbit_b32 v76, v35, v35, 16
	v_cndmask_b32_e64 v83, v76, v32, s[2:3]
	v_alignbit_b32 v77, v34, v34, 16
	v_lshlrev_b32_e32 v84, 16, v83
	v_and_b32_e32 v83, 0xffff0000, v83
	v_cndmask_b32_e64 v82, v77, v33, s[2:3]
	v_mul_f32_e32 v72, v246, v84
	v_mul_f32_e32 v73, v247, v83
	v_cvt_pk_bf16_f32 v72, v72, v73
	v_lshlrev_b32_e32 v73, 16, v82
	v_mul_f32_e32 v73, v248, v73
	v_and_b32_e32 v74, 0xffff0000, v82
	v_mul_f32_e32 v74, v249, v74
	v_cvt_pk_bf16_f32 v73, v73, v74
	v_lshlrev_b32_e32 v74, 16, v81
	v_and_b32_e32 v75, 0xffff0000, v81
	v_mul_f32_e32 v74, v250, v74
	v_mul_f32_e32 v75, v251, v75
	v_cvt_pk_bf16_f32 v74, v74, v75
	v_lshlrev_b32_e32 v75, 16, v80
	v_mul_f32_e32 v75, v252, v75
	v_and_b32_e32 v76, 0xffff0000, v80
	v_mul_f32_e32 v76, v253, v76
	v_cvt_pk_bf16_f32 v75, v75, v76
	ds_write_b128 v195, v[72:75]
	s_waitcnt vmcnt(4)
	ds_write_b128 v196, v[36:39]
	s_waitcnt vmcnt(3)
	ds_write_b128 v196, v[40:43] offset:34816
	s_waitcnt vmcnt(2)
	v_alignbit_b32 v72, v45, v45, 16
	v_alignbit_b32 v73, v44, v44, 16
	v_cndmask_b32_e64 v80, v73, v47, s[2:3]
	v_cndmask_b32_e64 v81, v72, v46, s[2:3]
	v_alignbit_b32 v76, v47, v47, 16
	v_cndmask_b32_e64 v83, v76, v44, s[2:3]
	v_alignbit_b32 v77, v46, v46, 16
	v_lshlrev_b32_e32 v84, 16, v83
	v_and_b32_e32 v83, 0xffff0000, v83
	v_cndmask_b32_e64 v82, v77, v45, s[2:3]
	v_mul_f32_e32 v72, v246, v84
	v_mul_f32_e32 v73, v247, v83
	v_cvt_pk_bf16_f32 v72, v72, v73
	v_lshlrev_b32_e32 v73, 16, v82
	v_mul_f32_e32 v73, v248, v73
	v_and_b32_e32 v74, 0xffff0000, v82
	v_mul_f32_e32 v74, v249, v74
	v_cvt_pk_bf16_f32 v73, v73, v74
	v_lshlrev_b32_e32 v74, 16, v81
	v_and_b32_e32 v75, 0xffff0000, v81
	v_mul_f32_e32 v74, v250, v74
	v_mul_f32_e32 v75, v251, v75
	v_cvt_pk_bf16_f32 v74, v74, v75
	v_lshlrev_b32_e32 v75, 16, v80
	v_mul_f32_e32 v75, v252, v75
	v_and_b32_e32 v76, 0xffff0000, v80
	v_mul_f32_e32 v76, v253, v76
	v_cvt_pk_bf16_f32 v75, v75, v76
	ds_write_b128 v197, v[72:75]
	s_waitcnt vmcnt(1)
	v_alignbit_b32 v72, v51, v51, 16
	v_alignbit_b32 v73, v50, v50, 16
	v_alignbit_b32 v74, v49, v49, 16
	v_alignbit_b32 v75, v48, v48, 16
	v_cndmask_b32_e64 v75, v75, v51, s[2:3]
	v_cndmask_b32_e64 v74, v74, v50, s[2:3]
	v_cndmask_b32_e64 v73, v73, v49, s[2:3]
	v_cndmask_b32_e64 v72, v72, v48, s[2:3]
	v_add_u32_e32 v76, v168, v188
	ds_write_b128 v76, v[72:75]
	s_waitcnt vmcnt(0)
	v_alignbit_b32 v72, v55, v55, 16
	v_alignbit_b32 v73, v54, v54, 16
	v_alignbit_b32 v74, v53, v53, 16
	v_alignbit_b32 v75, v52, v52, 16
	v_cndmask_b32_e64 v75, v75, v55, s[2:3]
	v_cndmask_b32_e64 v74, v74, v54, s[2:3]
	v_cndmask_b32_e64 v73, v73, v53, s[2:3]
	v_cndmask_b32_e64 v72, v72, v52, s[2:3]
	v_add_u32_e32 v76, v168, v191
	v_mov_b32_e32 v88, 0
	ds_write_b128 v76, v[72:75]
	s_mov_b32 s85, 0
	v_mov_b32_e32 v89, v88
	v_mov_b32_e32 v90, v88
	v_mov_b32_e32 v91, v88
	v_mov_b32_e32 v92, v88
	v_mov_b32_e32 v93, v88
	v_mov_b32_e32 v94, v88
	v_mov_b32_e32 v95, v88
	v_mov_b32_e32 v100, v88
	v_mov_b32_e32 v101, v88
	v_mov_b32_e32 v102, v88
	v_mov_b32_e32 v103, v88
	v_mov_b32_e32 v108, v88
	v_mov_b32_e32 v109, v88
	v_mov_b32_e32 v110, v88
	v_mov_b32_e32 v111, v88
	v_mov_b32_e32 v96, v88
	v_mov_b32_e32 v97, v88
	v_mov_b32_e32 v98, v88
	v_mov_b32_e32 v99, v88
	v_mov_b32_e32 v104, v88
	v_mov_b32_e32 v105, v88
	v_mov_b32_e32 v106, v88
	v_mov_b32_e32 v107, v88
	v_mov_b32_e32 v112, v88
	v_mov_b32_e32 v113, v88
	v_mov_b32_e32 v114, v88
	v_mov_b32_e32 v115, v88
	v_mov_b32_e32 v116, v88
	v_mov_b32_e32 v117, v88
	v_mov_b32_e32 v118, v88
	v_mov_b32_e32 v119, v88
	v_mov_b32_e32 v72, v88
	v_mov_b32_e32 v73, v88
	v_mov_b32_e32 v74, v88
	v_mov_b32_e32 v75, v88
	v_mov_b32_e32 v76, v88
	v_mov_b32_e32 v77, v88
	v_mov_b32_e32 v78, v88
	v_mov_b32_e32 v79, v88
	v_mov_b32_e32 v80, v88
	v_mov_b32_e32 v81, v88
	v_mov_b32_e32 v82, v88
	v_mov_b32_e32 v83, v88
	v_mov_b32_e32 v84, v88
	v_mov_b32_e32 v85, v88
	v_mov_b32_e32 v86, v88
	v_mov_b32_e32 v87, v88
	s_waitcnt lgkmcnt(0)
	s_barrier
	s_add_i32 s99, s84, 1
	s_cmp_ge_u32 s99, s95
	s_cbranch_scc1 .Lpf_skip
	s_lshl_b32 s100, s99, 7
	s_sub_i32 s101, s94, s100
	s_and_b64 s[86:87], s[2:3], exec
	s_cselect_b32 s100, s100, s101
	s_add_i32 s100, s100, s89
	s_ashr_i32 s101, s100, 7
	v_add_u32_e32 v0, s100, v148
	v_add_u32_e32 v12, s100, v150
	v_add_u32_e32 v24, s100, v151
	v_add_u32_e32 v36, s100, v152
	v_ashrrev_i32_e32 v1, 31, v0
	v_mad_i64_i32 v[8:9], s[86:87], s101, v149, v[136:137]
	v_ashrrev_i32_e32 v13, 31, v12
	v_mad_i64_i32 v[20:21], s[86:87], s101, v149, v[138:139]
	v_ashrrev_i32_e32 v25, 31, v24
	v_mad_i64_i32 v[32:33], s[86:87], s101, v149, v[140:141]
	v_ashrrev_i32_e32 v37, 31, v36
	v_mad_i64_i32 v[46:47], s[86:87], s101, v149, v[142:143]
	v_lshlrev_b64 v[0:1], 8, v[0:1]
	v_lshlrev_b64 v[44:45], 8, v[8:9]
	v_lshlrev_b64 v[12:13], 8, v[12:13]
	v_lshlrev_b64 v[52:53], 8, v[20:21]
	v_lshlrev_b64 v[24:25], 8, v[24:25]
	v_lshlrev_b64 v[32:33], 8, v[32:33]
	v_lshlrev_b64 v[36:37], 8, v[36:37]
	v_lshlrev_b64 v[46:47], 8, v[46:47]
	v_lshl_add_u64 v[2:3], v[128:129], 0, v[0:1]
	v_lshl_add_u64 v[4:5], v[130:131], 0, v[0:1]
	v_lshl_add_u64 v[8:9], v[132:133], 0, v[44:45]
	v_lshl_add_u64 v[14:15], v[128:129], 0, v[12:13]
	v_lshl_add_u64 v[16:17], v[130:131], 0, v[12:13]
	v_lshl_add_u64 v[20:21], v[132:133], 0, v[52:53]
	v_lshl_add_u64 v[26:27], v[128:129], 0, v[24:25]
	v_lshl_add_u64 v[28:29], v[130:131], 0, v[24:25]
	v_lshl_add_u64 v[32:33], v[132:133], 0, v[32:33]
	v_lshl_add_u64 v[38:39], v[128:129], 0, v[36:37]
	v_lshl_add_u64 v[40:41], v[130:131], 0, v[36:37]
	v_lshl_add_u64 v[46:47], v[132:133], 0, v[46:47]
	v_lshl_add_u64 v[48:49], v[144:145], 0, v[44:45]
	v_lshl_add_u64 v[52:53], v[144:145], 0, v[52:53]
	global_load_dwordx4 v[0:3], v[2:3], off
	s_nop 0
	global_load_dwordx4 v[4:7], v[4:5], off
	s_nop 0
	global_load_dwordx4 v[8:11], v[8:9], off
	s_nop 0
	global_load_dwordx4 v[12:15], v[14:15], off
	s_nop 0
	global_load_dwordx4 v[16:19], v[16:17], off
	s_nop 0
	global_load_dwordx4 v[20:23], v[20:21], off
	s_nop 0
	global_load_dwordx4 v[24:27], v[26:27], off
	s_nop 0
	global_load_dwordx4 v[28:31], v[28:29], off
	s_nop 0
	global_load_dwordx4 v[32:35], v[32:33], off
	s_nop 0
	global_load_dwordx4 v[36:39], v[38:39], off
	s_nop 0
	global_load_dwordx4 v[40:43], v[40:41], off
	s_nop 0
	global_load_dwordx4 v[44:47], v[46:47], off
	s_nop 0
	global_load_dwordx4 v[48:51], v[48:49], off
	s_nop 0
	global_load_dwordx4 v[52:55], v[52:53], off
	s_and_saveexec_b64 s[86:87], s[0:1]
	s_cbranch_execz .Lpf_215
	v_add_u32_e32 v120, s100, v153
	s_waitcnt lgkmcnt(0)
	v_ashrrev_i32_e32 v121, 31, v120
	v_readlane_b32 s100, v255, 10
	v_lshlrev_b64 v[120:121], 6, v[120:121]
	v_readlane_b32 s101, v255, 11
	s_nop 1
	v_lshl_add_u64 v[120:121], s[100:101], 0, v[120:121]
	global_load_dword v154, v[120:121], off
	global_load_dword v155, v[120:121], off offset:16

.LBB0_216:
	v_add_u32_e32 v120, s96, v174
	ds_read_b128 v[124:127], v120
	ds_read_b32 v202, v198
	ds_read_b32 v246, v209
	ds_read_b32 v247, v210
	ds_read_b32 v248, v211
	s_waitcnt lgkmcnt(0)
	v_sub_f32_e32 v121, v124, v202
	v_sub_f32_e32 v122, v125, v202
	v_exp_f32_e32 v219, v121
	v_exp_f32_e32 v220, v122
	ds_read_b128 v[120:123], v120 offset:64
	v_sub_f32_e32 v221, v126, v202
	v_sub_f32_e32 v222, v127, v202
	v_exp_f32_e32 v221, v221
	s_waitcnt lgkmcnt(0)
	v_sub_f32_e32 v223, v120, v202
	v_exp_f32_e32 v222, v222
	v_sub_f32_e32 v224, v121, v202
	v_cndmask_b32_e64 v219, v219, 0, s[18:19]
	v_exp_f32_e32 v223, v223
	v_sub_f32_e32 v225, v122, v202
	v_cndmask_b32_e64 v220, 0, v220, s[20:21]
	v_fma_f32 v227, v116, v219, 0
	v_exp_f32_e32 v224, v224
	v_sub_f32_e32 v202, v123, v202
	v_fmac_f32_e32 v227, v117, v220
	v_cndmask_b32_e64 v221, v221, 0, s[22:23]
	v_exp_f32_e32 v225, v225
	v_fmac_f32_e32 v227, v118, v221
	v_cndmask_b32_e64 v222, v222, 0, s[24:25]
	v_exp_f32_e32 v202, v202
	v_fmac_f32_e32 v227, v119, v222
	v_cndmask_b32_e64 v223, v223, 0, s[26:27]
	v_fmac_f32_e32 v227, v108, v223
	v_cndmask_b32_e64 v224, v224, 0, s[28:29]
	v_fmac_f32_e32 v227, v109, v224
	v_cndmask_b32_e64 v225, v225, 0, s[30:31]
	v_fmac_f32_e32 v227, v110, v225
	v_cndmask_b32_e64 v226, v202, 0, s[34:35]
	v_fmac_f32_e32 v227, v111, v226
	v_mov_b32_e32 v202, v227
	s_nop 1
	v_permlane16_swap_b32_e32 v227, v202
	v_add_f32_e32 v227, v227, v202
	v_mov_b32_e32 v228, v227
	s_nop 1
	v_permlane32_swap_b32_e32 v227, v228
	s_and_saveexec_b64 s[86:87], s[8:9]
	s_cbranch_execz .LBB0_218
	v_add_f32_e32 v202, v227, v228
	ds_write_b32 v199, v202
.LBB0_218:
	s_or_b64 exec, exec, s[86:87]
	v_mov_b32_e32 v202, v246
	s_nop 0
	v_sub_f32_e32 v227, v124, v202
	v_sub_f32_e32 v228, v125, v202
	v_sub_f32_e32 v229, v126, v202
	v_exp_f32_e32 v227, v227
	v_exp_f32_e32 v228, v228
	v_sub_f32_e32 v230, v127, v202
	v_exp_f32_e32 v229, v229
	v_sub_f32_e32 v231, v120, v202
	v_exp_f32_e32 v230, v230
	v_sub_f32_e32 v232, v121, v202
	v_cndmask_b32_e64 v227, v227, 0, s[36:37]
	v_exp_f32_e32 v231, v231
	v_sub_f32_e32 v233, v122, v202
	v_cndmask_b32_e64 v228, 0, v228, s[38:39]
	v_fma_f32 v235, v112, v227, 0
	v_exp_f32_e32 v232, v232
	v_sub_f32_e32 v202, v123, v202
	v_fmac_f32_e32 v235, v113, v228
	v_cndmask_b32_e64 v229, v229, 0, s[40:41]
	v_exp_f32_e32 v233, v233
	v_fmac_f32_e32 v235, v114, v229
	v_cndmask_b32_e64 v230, v230, 0, s[42:43]
	v_exp_f32_e32 v202, v202
	v_fmac_f32_e32 v235, v115, v230
	v_cndmask_b32_e64 v231, v231, 0, s[18:19]
	v_fmac_f32_e32 v235, v100, v231
	v_cndmask_b32_e64 v232, v232, 0, s[44:45]
	v_fmac_f32_e32 v235, v101, v232
	v_cndmask_b32_e64 v233, v233, 0, s[46:47]
	v_fmac_f32_e32 v235, v102, v233
	v_cndmask_b32_e64 v234, v202, 0, s[48:49]
	v_fmac_f32_e32 v235, v103, v234
	v_mov_b32_e32 v202, v235
	s_nop 1
	v_permlane16_swap_b32_e32 v235, v202
	v_add_f32_e32 v235, v235, v202
	v_mov_b32_e32 v236, v235
	s_nop 1
	v_permlane32_swap_b32_e32 v235, v236
	s_and_saveexec_b64 s[86:87], s[8:9]
	s_cbranch_execz .LBB0_220
	v_add_f32_e32 v202, v235, v236
	ds_write_b32 v199, v202 offset:64
.LBB0_220:
	s_or_b64 exec, exec, s[86:87]
	v_mov_b32_e32 v202, v247
	s_nop 0
	v_sub_f32_e32 v235, v124, v202
	v_sub_f32_e32 v236, v125, v202
	v_sub_f32_e32 v237, v126, v202
	v_exp_f32_e32 v235, v235
	v_exp_f32_e32 v236, v236
	v_sub_f32_e32 v238, v127, v202
	v_exp_f32_e32 v237, v237
	v_sub_f32_e32 v239, v120, v202
	v_exp_f32_e32 v238, v238
	v_sub_f32_e32 v240, v121, v202
	v_cndmask_b32_e64 v235, v235, 0, s[50:51]
	v_exp_f32_e32 v239, v239
	v_sub_f32_e32 v241, v122, v202
	v_cndmask_b32_e64 v236, 0, v236, s[52:53]
	v_fma_f32 v243, v104, v235, 0
	v_exp_f32_e32 v240, v240
	v_sub_f32_e32 v202, v123, v202
	v_fmac_f32_e32 v243, v105, v236
	v_cndmask_b32_e64 v237, v237, 0, s[54:55]
	v_exp_f32_e32 v241, v241
	v_fmac_f32_e32 v243, v106, v237
	v_cndmask_b32_e64 v238, v238, 0, s[56:57]
	v_exp_f32_e32 v202, v202
	v_fmac_f32_e32 v243, v107, v238
	v_cndmask_b32_e64 v239, v239, 0, s[58:59]
	v_fmac_f32_e32 v243, v92, v239
	v_cndmask_b32_e64 v240, v240, 0, s[60:61]
	v_fmac_f32_e32 v243, v93, v240
	v_cndmask_b32_e64 v241, v241, 0, s[62:63]
	v_fmac_f32_e32 v243, v94, v241
	v_cndmask_b32_e64 v242, v202, 0, s[64:65]
	v_fmac_f32_e32 v243, v95, v242
	v_mov_b32_e32 v202, v243
	s_nop 1
	v_permlane16_swap_b32_e32 v243, v202
	v_add_f32_e32 v243, v243, v202
	v_mov_b32_e32 v244, v243
	s_nop 1
	v_permlane32_swap_b32_e32 v243, v244
	s_and_saveexec_b64 s[86:87], s[8:9]
	s_cbranch_execz .LBB0_222
	v_add_f32_e32 v202, v243, v244
	ds_write_b32 v199, v202 offset:128
.LBB0_222:
	s_or_b64 exec, exec, s[86:87]
	v_mov_b32_e32 v202, v248
	s_nop 0
	v_sub_f32_e32 v124, v124, v202
	v_sub_f32_e32 v125, v125, v202
	v_sub_f32_e32 v126, v126, v202
	v_exp_f32_e32 v124, v124
	v_exp_f32_e32 v125, v125
	v_sub_f32_e32 v127, v127, v202
	v_exp_f32_e32 v126, v126
	v_sub_f32_e32 v120, v120, v202
	v_exp_f32_e32 v127, v127
	v_sub_f32_e32 v121, v121, v202
	v_cndmask_b32_e64 v124, v124, 0, s[66:67]
	v_exp_f32_e32 v120, v120
	v_sub_f32_e32 v122, v122, v202
	v_cndmask_b32_e64 v125, 0, v125, s[68:69]
	v_fma_f32 v243, v96, v124, 0
	v_exp_f32_e32 v121, v121
	v_sub_f32_e32 v123, v123, v202
	v_fmac_f32_e32 v243, v97, v125
	v_cndmask_b32_e64 v126, v126, 0, s[70:71]
	v_exp_f32_e32 v122, v122
	v_fmac_f32_e32 v243, v98, v126
	v_cndmask_b32_e64 v127, v127, 0, s[72:73]
	v_exp_f32_e32 v123, v123
	v_fmac_f32_e32 v243, v99, v127
	v_cndmask_b32_e64 v120, v120, 0, s[74:75]
	v_fmac_f32_e32 v243, v88, v120
	v_cndmask_b32_e64 v121, v121, 0, s[76:77]
	v_fmac_f32_e32 v243, v89, v121
	v_cndmask_b32_e64 v122, v122, 0, s[78:79]
	v_fmac_f32_e32 v243, v90, v122
	v_cndmask_b32_e64 v123, v123, 0, s[80:81]
	v_fmac_f32_e32 v243, v91, v123
	v_mov_b32_e32 v202, v243
	s_nop 1
	v_permlane16_swap_b32_e32 v243, v202
	v_add_f32_e32 v243, v243, v202
	v_mov_b32_e32 v244, v243
	s_nop 1
	v_permlane32_swap_b32_e32 v243, v244
	s_and_saveexec_b64 s[86:87], s[8:9]
	s_cbranch_execz .LBB0_224
	v_add_f32_e32 v202, v243, v244
	ds_write_b32 v199, v202 offset:192
